# P0: mod GEMV re-tiled to 192 items of 64 columns (hand-written, pipelined loads), GEMV and early transposes moved off the low-numbered workgroups
# speedup vs baseline: 1.0098x; 1.0098x over previous
; __device__ __forceinline__ float silu_f(float v) { return v / (1.0f + __expf(-v)); }
; __device__ __forceinline__ void p0_prologue(const Args& a, LAS unsigned char* lds, int G) {
;     ...
;     for (int it = blockIdx.x; it < 48; it += G) {
;         if (!have_silu) {
;             for (int k = tid; k < 1024; k += NTHR) { sv[k] = silu_f(a.c[k]); sv[1024 + k] = silu_f(a.c[1024 + k]); sv[2048 + k] = silu_f(a.c_ctx[k]); }
;             have_silu = true;
;         }
;         __syncthreads();
;         const int layer = it / 24, cgp = it % 24, c0 = cgp * 256;
;         const float* W = a.w_mod + (size_t)layer * 1024 * 6144 + c0 + 4 * lane;
;         f32x4 a0 = {0, 0, 0, 0}, a1 = {0, 0, 0, 0}, a2 = {0, 0, 0, 0};
;         const int kb = wid * 128;
; #pragma unroll 8
.LBB0_13:
	s_or_b64 exec, exec, s[0:1]
	s_lshr_b32 s14, s14, 6
	s_sub_i32 s99, s2, 64
	s_cmp_gt_u32 s99, 0xbf
	v_and_b32_e32 v1, 63, v206
	s_cbranch_scc1 .LBB0_25
	v_readlane_b32 s16, v252, 17
	s_lshl_b32 s0, s14, 9
	v_lshlrev_b32_e32 v2, 2, v206
	v_mov_b32_e32 v3, 0
	v_readlane_b32 s18, v252, 19
	v_readlane_b32 s19, v252, 20
	s_add_i32 s15, s0, 0
	s_mul_i32 s0, s14, 0xa00
	v_lshl_add_u64 v[4:5], s[18:19], 0, v[2:3]
	s_mov_b64 s[4:5], 0x1000
	s_lshl_b32 s6, s14, 7
	s_add_i32 s0, s15, s0
	v_readlane_b32 s24, v252, 25
	v_lshl_add_u64 v[14:15], v[4:5], 0, s[4:5]
	s_mul_i32 s4, s14, 0x300000
	v_readlane_b32 s22, v252, 23
	v_readlane_b32 s23, v252, 24
	v_readlane_b32 s25, v252, 26
	s_mul_hi_u32 s5, s6, 0x6000
	s_add_u32 s4, s24, s4
	v_lshl_add_u32 v22, v1, 4, s0
	s_movk_i32 s0, 0x100
	v_add_u32_e32 v24, 0, v2
	v_readlane_b32 s17, v252, 18
	v_readlane_b32 s20, v252, 21
	v_readlane_b32 s21, v252, 22
	v_lshl_add_u64 v[16:17], s[22:23], 0, v[2:3]
	v_lshlrev_b32_e32 v2, 4, v1
	s_addc_u32 s5, s25, s5
	v_cmp_gt_u32_e64 s[0:1], s0, v206
	v_or_b32_e32 v23, 0x1800, v206
	v_add_u32_e32 v25, 0xfffffe00, v206
	s_movk_i32 s16, 0x6000
	v_lshl_add_u64 v[18:19], s[4:5], 0, v[2:3]
	s_mov_b64 s[4:5], 0
	s_mov_b64 s[10:11], 0x800
	s_mov_b32 s17, 0xc000
	s_mov_b32 s18, 0x12000
	s_mov_b32 s19, 0x18000
	s_mov_b32 s20, 0x1e000
	s_mov_b32 s21, 0x24000
	s_mov_b32 s22, 0x2a000
	s_mov_b32 s23, s99
	v_readlane_b32 s26, v252, 27
	v_readlane_b32 s27, v252, 28
	v_readlane_b32 s28, v252, 29
	v_readlane_b32 s29, v252, 30
	v_readlane_b32 s30, v252, 31
	v_readlane_b32 s31, v252, 32
	s_branch .LBB0_16

; __device__ __forceinline__ void p0_prologue(const Args& a, LAS unsigned char* lds, int G) {
;     ...
;     for (int it = blockIdx.x; it < 48; it += G) {
.Lgemv_latch:
	s_add_i32 s23, s23, s86
	s_cmp_gt_i32 s23, 0xbf
	s_mov_b64 s[4:5], -1
	s_cbranch_scc1 .LBB0_25

; __device__ __forceinline__ void p0_prologue(const Args& a, LAS unsigned char* lds, int G) {
;     ...
;         const int layer = it / 24, cgp = it % 24, c0 = cgp * 256;
;         const float* W = a.w_mod + (size_t)layer * 1024 * 6144 + c0 + 4 * lane;
;         f32x4 a0 = {0, 0, 0, 0}, a1 = {0, 0, 0, 0}, a2 = {0, 0, 0, 0};
;         const int kb = wid * 128;
; #pragma unroll 8
;         for (int k = 0; k < 128; ++k) {
;             const f32x4 w = __builtin_nontemporal_load((const f32x4*)(W + (size_t)(kb + k) * 6144));
;             const float s0 = sv[kb + k], s1 = sv[1024 + kb + k], s2 = sv[2048 + kb + k];
;             a0 += w * s0; a1 += w * s1; a2 += w * s2;
;         }
.LBB0_20:
	s_cmp_ge_u32 s23, 0x60
	s_cselect_b32 s12, 1, 0
	s_mul_i32 s13, s12, 0x60
	s_sub_u32 s13, s23, s13
	s_lshl_b32 s13, s13, 6
	v_readlane_b32 s24, v252, 25
	v_readlane_b32 s25, v252, 26
	s_lshl_b32 s4, s12, 10
	s_lshl_b32 s5, s14, 7
	s_add_u32 s4, s4, s5
	s_mul_i32 s4, s4, 0x6000
	s_lshl_b32 s52, s13, 2
	s_add_u32 s4, s4, s52
	s_add_u32 s24, s24, s4
	s_addc_u32 s25, s25, 0
	v_and_b32_e32 v2, 63, v206
	v_lshrrev_b32_e32 v3, 4, v2
	v_and_b32_e32 v4, 15, v2
	v_mul_u32_u24_e32 v5, 0xc0000, v3
	v_lshl_add_u32 v5, v4, 4, v5
	s_lshl_b32 s53, s14, 9
	v_lshlrev_b32_e32 v6, 7, v3
	v_add_u32_e32 v6, s53, v6
	v_mov_b32_e32 v8, 0
	v_mov_b32_e32 v9, 0
	v_mov_b32_e32 v10, 0
	v_mov_b32_e32 v11, 0
	v_mov_b32_e32 v12, 0
	v_mov_b32_e32 v13, 0
	v_mov_b32_e32 v14, 0
	v_mov_b32_e32 v15, 0
	v_mov_b32_e32 v16, 0
	v_mov_b32_e32 v17, 0
	v_mov_b32_e32 v18, 0
	v_mov_b32_e32 v19, 0
	s_waitcnt lgkmcnt(0)
	s_barrier
	global_load_dwordx4 v[20:23], v5, s[24:25] nt
	s_add_u32 s24, s24, 0x6000
	s_addc_u32 s25, s25, 0
	global_load_dwordx4 v[24:27], v5, s[24:25] nt
	s_add_u32 s24, s24, 0x6000
	s_addc_u32 s25, s25, 0
	global_load_dwordx4 v[28:31], v5, s[24:25] nt
	s_add_u32 s24, s24, 0x6000
	s_addc_u32 s25, s25, 0
	global_load_dwordx4 v[32:35], v5, s[24:25] nt
	s_add_u32 s24, s24, 0x6000
	s_addc_u32 s25, s25, 0
	global_load_dwordx4 v[36:39], v5, s[24:25] nt
	s_add_u32 s24, s24, 0x6000
	s_addc_u32 s25, s25, 0
	global_load_dwordx4 v[40:43], v5, s[24:25] nt
	s_add_u32 s24, s24, 0x6000
	s_addc_u32 s25, s25, 0
	global_load_dwordx4 v[44:47], v5, s[24:25] nt
	s_add_u32 s24, s24, 0x6000
	s_addc_u32 s25, s25, 0
	global_load_dwordx4 v[48:51], v5, s[24:25] nt
	s_add_u32 s24, s24, 0x6000
	s_addc_u32 s25, s25, 0
	ds_read_b128 v[68:71], v6 offset:0
	ds_read_b128 v[72:75], v6 offset:4096
	ds_read_b128 v[76:79], v6 offset:8192
	global_load_dwordx4 v[52:55], v5, s[24:25] nt
	s_add_u32 s24, s24, 0x6000
	s_addc_u32 s25, s25, 0
	global_load_dwordx4 v[56:59], v5, s[24:25] nt
	s_add_u32 s24, s24, 0x6000
	s_addc_u32 s25, s25, 0
	global_load_dwordx4 v[60:63], v5, s[24:25] nt
	s_add_u32 s24, s24, 0x6000
	s_addc_u32 s25, s25, 0
	global_load_dwordx4 v[64:67], v5, s[24:25] nt
	s_add_u32 s24, s24, 0x6000
	s_addc_u32 s25, s25, 0
	ds_read_b128 v[80:83], v6 offset:16
	ds_read_b128 v[84:87], v6 offset:4112
	ds_read_b128 v[88:91], v6 offset:8208
	s_waitcnt vmcnt(8)
	s_waitcnt lgkmcnt(3)
	v_pk_fma_f32 v[8:9], v[20:21], v[68:69], v[8:9] op_sel_hi:[1,0,1]
	v_pk_fma_f32 v[10:11], v[22:23], v[68:69], v[10:11] op_sel_hi:[1,0,1]
	v_pk_fma_f32 v[12:13], v[20:21], v[72:73], v[12:13] op_sel_hi:[1,0,1]
	v_pk_fma_f32 v[14:15], v[22:23], v[72:73], v[14:15] op_sel_hi:[1,0,1]
	v_pk_fma_f32 v[16:17], v[20:21], v[76:77], v[16:17] op_sel_hi:[1,0,1]
	v_pk_fma_f32 v[18:19], v[22:23], v[76:77], v[18:19] op_sel_hi:[1,0,1]
	v_pk_fma_f32 v[8:9], v[24:25], v[68:69], v[8:9] op_sel:[0,1,0]
	v_pk_fma_f32 v[10:11], v[26:27], v[68:69], v[10:11] op_sel:[0,1,0]
	v_pk_fma_f32 v[12:13], v[24:25], v[72:73], v[12:13] op_sel:[0,1,0]
	v_pk_fma_f32 v[14:15], v[26:27], v[72:73], v[14:15] op_sel:[0,1,0]
	v_pk_fma_f32 v[16:17], v[24:25], v[76:77], v[16:17] op_sel:[0,1,0]
	v_pk_fma_f32 v[18:19], v[26:27], v[76:77], v[18:19] op_sel:[0,1,0]
	v_pk_fma_f32 v[8:9], v[28:29], v[70:71], v[8:9] op_sel_hi:[1,0,1]
	v_pk_fma_f32 v[10:11], v[30:31], v[70:71], v[10:11] op_sel_hi:[1,0,1]
	v_pk_fma_f32 v[12:13], v[28:29], v[74:75], v[12:13] op_sel_hi:[1,0,1]
	v_pk_fma_f32 v[14:15], v[30:31], v[74:75], v[14:15] op_sel_hi:[1,0,1]
	v_pk_fma_f32 v[16:17], v[28:29], v[78:79], v[16:17] op_sel_hi:[1,0,1]
	v_pk_fma_f32 v[18:19], v[30:31], v[78:79], v[18:19] op_sel_hi:[1,0,1]
	v_pk_fma_f32 v[8:9], v[32:33], v[70:71], v[8:9] op_sel:[0,1,0]
	v_pk_fma_f32 v[10:11], v[34:35], v[70:71], v[10:11] op_sel:[0,1,0]
	v_pk_fma_f32 v[12:13], v[32:33], v[74:75], v[12:13] op_sel:[0,1,0]
	v_pk_fma_f32 v[14:15], v[34:35], v[74:75], v[14:15] op_sel:[0,1,0]
	v_pk_fma_f32 v[16:17], v[32:33], v[78:79], v[16:17] op_sel:[0,1,0]
	v_pk_fma_f32 v[18:19], v[34:35], v[78:79], v[18:19] op_sel:[0,1,0]
	global_load_dwordx4 v[20:23], v5, s[24:25] nt
	s_add_u32 s24, s24, 0x6000
	s_addc_u32 s25, s25, 0
	global_load_dwordx4 v[24:27], v5, s[24:25] nt
	s_add_u32 s24, s24, 0x6000
	s_addc_u32 s25, s25, 0
	global_load_dwordx4 v[28:31], v5, s[24:25] nt
	s_add_u32 s24, s24, 0x6000
	s_addc_u32 s25, s25, 0
	global_load_dwordx4 v[32:35], v5, s[24:25] nt
	s_add_u32 s24, s24, 0x6000
	s_addc_u32 s25, s25, 0
	ds_read_b128 v[68:71], v6 offset:32
	ds_read_b128 v[72:75], v6 offset:4128
	ds_read_b128 v[76:79], v6 offset:8224
	s_waitcnt vmcnt(8)
	s_waitcnt lgkmcnt(3)
; __device__ __forceinline__ void p0_prologue(const Args& a, LAS unsigned char* lds, int G) {
;     ...
; #pragma unroll 8
;         for (int k = 0; k < 128; ++k) {
;             const f32x4 w = __builtin_nontemporal_load((const f32x4*)(W + (size_t)(kb + k) * 6144));
;             const float s0 = sv[kb + k], s1 = sv[1024 + kb + k], s2 = sv[2048 + kb + k];
;             a0 += w * s0; a1 += w * s1; a2 += w * s2;
;         }
	v_pk_fma_f32 v[8:9], v[36:37], v[80:81], v[8:9] op_sel_hi:[1,0,1]
	v_pk_fma_f32 v[10:11], v[38:39], v[80:81], v[10:11] op_sel_hi:[1,0,1]
	v_pk_fma_f32 v[12:13], v[36:37], v[84:85], v[12:13] op_sel_hi:[1,0,1]
	v_pk_fma_f32 v[14:15], v[38:39], v[84:85], v[14:15] op_sel_hi:[1,0,1]
	v_pk_fma_f32 v[16:17], v[36:37], v[88:89], v[16:17] op_sel_hi:[1,0,1]
	v_pk_fma_f32 v[18:19], v[38:39], v[88:89], v[18:19] op_sel_hi:[1,0,1]
	v_pk_fma_f32 v[8:9], v[40:41], v[80:81], v[8:9] op_sel:[0,1,0]
	v_pk_fma_f32 v[10:11], v[42:43], v[80:81], v[10:11] op_sel:[0,1,0]
	v_pk_fma_f32 v[12:13], v[40:41], v[84:85], v[12:13] op_sel:[0,1,0]
	v_pk_fma_f32 v[14:15], v[42:43], v[84:85], v[14:15] op_sel:[0,1,0]
	v_pk_fma_f32 v[16:17], v[40:41], v[88:89], v[16:17] op_sel:[0,1,0]
	v_pk_fma_f32 v[18:19], v[42:43], v[88:89], v[18:19] op_sel:[0,1,0]
	v_pk_fma_f32 v[8:9], v[44:45], v[82:83], v[8:9] op_sel_hi:[1,0,1]
	v_pk_fma_f32 v[10:11], v[46:47], v[82:83], v[10:11] op_sel_hi:[1,0,1]
	v_pk_fma_f32 v[12:13], v[44:45], v[86:87], v[12:13] op_sel_hi:[1,0,1]
	v_pk_fma_f32 v[14:15], v[46:47], v[86:87], v[14:15] op_sel_hi:[1,0,1]
	v_pk_fma_f32 v[16:17], v[44:45], v[90:91], v[16:17] op_sel_hi:[1,0,1]
	v_pk_fma_f32 v[18:19], v[46:47], v[90:91], v[18:19] op_sel_hi:[1,0,1]
	v_pk_fma_f32 v[8:9], v[48:49], v[82:83], v[8:9] op_sel:[0,1,0]
	v_pk_fma_f32 v[10:11], v[50:51], v[82:83], v[10:11] op_sel:[0,1,0]
	v_pk_fma_f32 v[12:13], v[48:49], v[86:87], v[12:13] op_sel:[0,1,0]
	v_pk_fma_f32 v[14:15], v[50:51], v[86:87], v[14:15] op_sel:[0,1,0]
	v_pk_fma_f32 v[16:17], v[48:49], v[90:91], v[16:17] op_sel:[0,1,0]
	v_pk_fma_f32 v[18:19], v[50:51], v[90:91], v[18:19] op_sel:[0,1,0]
	global_load_dwordx4 v[36:39], v5, s[24:25] nt
	s_add_u32 s24, s24, 0x6000
	s_addc_u32 s25, s25, 0
	global_load_dwordx4 v[40:43], v5, s[24:25] nt
	s_add_u32 s24, s24, 0x6000
	s_addc_u32 s25, s25, 0
	global_load_dwordx4 v[44:47], v5, s[24:25] nt
	s_add_u32 s24, s24, 0x6000
	s_addc_u32 s25, s25, 0
	global_load_dwordx4 v[48:51], v5, s[24:25] nt
	s_add_u32 s24, s24, 0x6000
	s_addc_u32 s25, s25, 0
	ds_read_b128 v[80:83], v6 offset:48
	ds_read_b128 v[84:87], v6 offset:4144
	ds_read_b128 v[88:91], v6 offset:8240
	s_waitcnt vmcnt(8)
	s_waitcnt lgkmcnt(3)
	v_pk_fma_f32 v[8:9], v[52:53], v[68:69], v[8:9] op_sel_hi:[1,0,1]
	v_pk_fma_f32 v[10:11], v[54:55], v[68:69], v[10:11] op_sel_hi:[1,0,1]
	v_pk_fma_f32 v[12:13], v[52:53], v[72:73], v[12:13] op_sel_hi:[1,0,1]
	v_pk_fma_f32 v[14:15], v[54:55], v[72:73], v[14:15] op_sel_hi:[1,0,1]
	v_pk_fma_f32 v[16:17], v[52:53], v[76:77], v[16:17] op_sel_hi:[1,0,1]
	v_pk_fma_f32 v[18:19], v[54:55], v[76:77], v[18:19] op_sel_hi:[1,0,1]
	v_pk_fma_f32 v[8:9], v[56:57], v[68:69], v[8:9] op_sel:[0,1,0]
	v_pk_fma_f32 v[10:11], v[58:59], v[68:69], v[10:11] op_sel:[0,1,0]
	v_pk_fma_f32 v[12:13], v[56:57], v[72:73], v[12:13] op_sel:[0,1,0]
	v_pk_fma_f32 v[14:15], v[58:59], v[72:73], v[14:15] op_sel:[0,1,0]
	v_pk_fma_f32 v[16:17], v[56:57], v[76:77], v[16:17] op_sel:[0,1,0]
	v_pk_fma_f32 v[18:19], v[58:59], v[76:77], v[18:19] op_sel:[0,1,0]
	v_pk_fma_f32 v[8:9], v[60:61], v[70:71], v[8:9] op_sel_hi:[1,0,1]
	v_pk_fma_f32 v[10:11], v[62:63], v[70:71], v[10:11] op_sel_hi:[1,0,1]
	v_pk_fma_f32 v[12:13], v[60:61], v[74:75], v[12:13] op_sel_hi:[1,0,1]
	v_pk_fma_f32 v[14:15], v[62:63], v[74:75], v[14:15] op_sel_hi:[1,0,1]
	v_pk_fma_f32 v[16:17], v[60:61], v[78:79], v[16:17] op_sel_hi:[1,0,1]
	v_pk_fma_f32 v[18:19], v[62:63], v[78:79], v[18:19] op_sel_hi:[1,0,1]
	v_pk_fma_f32 v[8:9], v[64:65], v[70:71], v[8:9] op_sel:[0,1,0]
	v_pk_fma_f32 v[10:11], v[66:67], v[70:71], v[10:11] op_sel:[0,1,0]
	v_pk_fma_f32 v[12:13], v[64:65], v[74:75], v[12:13] op_sel:[0,1,0]
	v_pk_fma_f32 v[14:15], v[66:67], v[74:75], v[14:15] op_sel:[0,1,0]
	v_pk_fma_f32 v[16:17], v[64:65], v[78:79], v[16:17] op_sel:[0,1,0]
	v_pk_fma_f32 v[18:19], v[66:67], v[78:79], v[18:19] op_sel:[0,1,0]
	global_load_dwordx4 v[52:55], v5, s[24:25] nt
	s_add_u32 s24, s24, 0x6000
	s_addc_u32 s25, s25, 0
	global_load_dwordx4 v[56:59], v5, s[24:25] nt
	s_add_u32 s24, s24, 0x6000
	s_addc_u32 s25, s25, 0
	global_load_dwordx4 v[60:63], v5, s[24:25] nt
	s_add_u32 s24, s24, 0x6000
	s_addc_u32 s25, s25, 0
	global_load_dwordx4 v[64:67], v5, s[24:25] nt
	s_add_u32 s24, s24, 0x6000
	s_addc_u32 s25, s25, 0
	ds_read_b128 v[68:71], v6 offset:64
	ds_read_b128 v[72:75], v6 offset:4160
	ds_read_b128 v[76:79], v6 offset:8256
	s_waitcnt vmcnt(8)
	s_waitcnt lgkmcnt(3)
	v_pk_fma_f32 v[8:9], v[20:21], v[80:81], v[8:9] op_sel_hi:[1,0,1]
	v_pk_fma_f32 v[10:11], v[22:23], v[80:81], v[10:11] op_sel_hi:[1,0,1]
	v_pk_fma_f32 v[12:13], v[20:21], v[84:85], v[12:13] op_sel_hi:[1,0,1]
	v_pk_fma_f32 v[14:15], v[22:23], v[84:85], v[14:15] op_sel_hi:[1,0,1]
	v_pk_fma_f32 v[16:17], v[20:21], v[88:89], v[16:17] op_sel_hi:[1,0,1]
	v_pk_fma_f32 v[18:19], v[22:23], v[88:89], v[18:19] op_sel_hi:[1,0,1]
	v_pk_fma_f32 v[8:9], v[24:25], v[80:81], v[8:9] op_sel:[0,1,0]
	v_pk_fma_f32 v[10:11], v[26:27], v[80:81], v[10:11] op_sel:[0,1,0]
	v_pk_fma_f32 v[12:13], v[24:25], v[84:85], v[12:13] op_sel:[0,1,0]
	v_pk_fma_f32 v[14:15], v[26:27], v[84:85], v[14:15] op_sel:[0,1,0]
	v_pk_fma_f32 v[16:17], v[24:25], v[88:89], v[16:17] op_sel:[0,1,0]
	v_pk_fma_f32 v[18:19], v[26:27], v[88:89], v[18:19] op_sel:[0,1,0]
	v_pk_fma_f32 v[8:9], v[28:29], v[82:83], v[8:9] op_sel_hi:[1,0,1]
	v_pk_fma_f32 v[10:11], v[30:31], v[82:83], v[10:11] op_sel_hi:[1,0,1]
	v_pk_fma_f32 v[12:13], v[28:29], v[86:87], v[12:13] op_sel_hi:[1,0,1]
	v_pk_fma_f32 v[14:15], v[30:31], v[86:87], v[14:15] op_sel_hi:[1,0,1]
	v_pk_fma_f32 v[16:17], v[28:29], v[90:91], v[16:17] op_sel_hi:[1,0,1]
	v_pk_fma_f32 v[18:19], v[30:31], v[90:91], v[18:19] op_sel_hi:[1,0,1]
	v_pk_fma_f32 v[8:9], v[32:33], v[82:83], v[8:9] op_sel:[0,1,0]
	v_pk_fma_f32 v[10:11], v[34:35], v[82:83], v[10:11] op_sel:[0,1,0]
	v_pk_fma_f32 v[12:13], v[32:33], v[86:87], v[12:13] op_sel:[0,1,0]
	v_pk_fma_f32 v[14:15], v[34:35], v[86:87], v[14:15] op_sel:[0,1,0]
	v_pk_fma_f32 v[16:17], v[32:33], v[90:91], v[16:17] op_sel:[0,1,0]
	v_pk_fma_f32 v[18:19], v[34:35], v[90:91], v[18:19] op_sel:[0,1,0]
	global_load_dwordx4 v[20:23], v5, s[24:25] nt
	s_add_u32 s24, s24, 0x6000
	s_addc_u32 s25, s25, 0
	global_load_dwordx4 v[24:27], v5, s[24:25] nt
	s_add_u32 s24, s24, 0x6000
	s_addc_u32 s25, s25, 0
	global_load_dwordx4 v[28:31], v5, s[24:25] nt
	s_add_u32 s24, s24, 0x6000
	s_addc_u32 s25, s25, 0
	global_load_dwordx4 v[32:35], v5, s[24:25] nt
	s_add_u32 s24, s24, 0x6000
	s_addc_u32 s25, s25, 0
	ds_read_b128 v[80:83], v6 offset:80
	ds_read_b128 v[84:87], v6 offset:4176
	ds_read_b128 v[88:91], v6 offset:8272
	s_waitcnt vmcnt(8)
; __device__ __forceinline__ void p0_prologue(const Args& a, LAS unsigned char* lds, int G) {
;     ...
; #pragma unroll 8
;         for (int k = 0; k < 128; ++k) {
;             const f32x4 w = __builtin_nontemporal_load((const f32x4*)(W + (size_t)(kb + k) * 6144));
;             const float s0 = sv[kb + k], s1 = sv[1024 + kb + k], s2 = sv[2048 + kb + k];
;             a0 += w * s0; a1 += w * s1; a2 += w * s2;
;         }
	s_waitcnt lgkmcnt(3)
	v_pk_fma_f32 v[8:9], v[36:37], v[68:69], v[8:9] op_sel_hi:[1,0,1]
	v_pk_fma_f32 v[10:11], v[38:39], v[68:69], v[10:11] op_sel_hi:[1,0,1]
	v_pk_fma_f32 v[12:13], v[36:37], v[72:73], v[12:13] op_sel_hi:[1,0,1]
	v_pk_fma_f32 v[14:15], v[38:39], v[72:73], v[14:15] op_sel_hi:[1,0,1]
	v_pk_fma_f32 v[16:17], v[36:37], v[76:77], v[16:17] op_sel_hi:[1,0,1]
	v_pk_fma_f32 v[18:19], v[38:39], v[76:77], v[18:19] op_sel_hi:[1,0,1]
	v_pk_fma_f32 v[8:9], v[40:41], v[68:69], v[8:9] op_sel:[0,1,0]
	v_pk_fma_f32 v[10:11], v[42:43], v[68:69], v[10:11] op_sel:[0,1,0]
	v_pk_fma_f32 v[12:13], v[40:41], v[72:73], v[12:13] op_sel:[0,1,0]
	v_pk_fma_f32 v[14:15], v[42:43], v[72:73], v[14:15] op_sel:[0,1,0]
	v_pk_fma_f32 v[16:17], v[40:41], v[76:77], v[16:17] op_sel:[0,1,0]
	v_pk_fma_f32 v[18:19], v[42:43], v[76:77], v[18:19] op_sel:[0,1,0]
	v_pk_fma_f32 v[8:9], v[44:45], v[70:71], v[8:9] op_sel_hi:[1,0,1]
	v_pk_fma_f32 v[10:11], v[46:47], v[70:71], v[10:11] op_sel_hi:[1,0,1]
	v_pk_fma_f32 v[12:13], v[44:45], v[74:75], v[12:13] op_sel_hi:[1,0,1]
	v_pk_fma_f32 v[14:15], v[46:47], v[74:75], v[14:15] op_sel_hi:[1,0,1]
	v_pk_fma_f32 v[16:17], v[44:45], v[78:79], v[16:17] op_sel_hi:[1,0,1]
	v_pk_fma_f32 v[18:19], v[46:47], v[78:79], v[18:19] op_sel_hi:[1,0,1]
	v_pk_fma_f32 v[8:9], v[48:49], v[70:71], v[8:9] op_sel:[0,1,0]
	v_pk_fma_f32 v[10:11], v[50:51], v[70:71], v[10:11] op_sel:[0,1,0]
	v_pk_fma_f32 v[12:13], v[48:49], v[74:75], v[12:13] op_sel:[0,1,0]
	v_pk_fma_f32 v[14:15], v[50:51], v[74:75], v[14:15] op_sel:[0,1,0]
	v_pk_fma_f32 v[16:17], v[48:49], v[78:79], v[16:17] op_sel:[0,1,0]
	v_pk_fma_f32 v[18:19], v[50:51], v[78:79], v[18:19] op_sel:[0,1,0]
	global_load_dwordx4 v[36:39], v5, s[24:25] nt
	s_add_u32 s24, s24, 0x6000
	s_addc_u32 s25, s25, 0
	global_load_dwordx4 v[40:43], v5, s[24:25] nt
	s_add_u32 s24, s24, 0x6000
	s_addc_u32 s25, s25, 0
	global_load_dwordx4 v[44:47], v5, s[24:25] nt
	s_add_u32 s24, s24, 0x6000
	s_addc_u32 s25, s25, 0
	global_load_dwordx4 v[48:51], v5, s[24:25] nt
	s_add_u32 s24, s24, 0x6000
	s_addc_u32 s25, s25, 0
	ds_read_b128 v[68:71], v6 offset:96
	ds_read_b128 v[72:75], v6 offset:4192
	ds_read_b128 v[76:79], v6 offset:8288
	s_waitcnt vmcnt(8)
	s_waitcnt lgkmcnt(3)
	v_pk_fma_f32 v[8:9], v[52:53], v[80:81], v[8:9] op_sel_hi:[1,0,1]
	v_pk_fma_f32 v[10:11], v[54:55], v[80:81], v[10:11] op_sel_hi:[1,0,1]
	v_pk_fma_f32 v[12:13], v[52:53], v[84:85], v[12:13] op_sel_hi:[1,0,1]
	v_pk_fma_f32 v[14:15], v[54:55], v[84:85], v[14:15] op_sel_hi:[1,0,1]
	v_pk_fma_f32 v[16:17], v[52:53], v[88:89], v[16:17] op_sel_hi:[1,0,1]
	v_pk_fma_f32 v[18:19], v[54:55], v[88:89], v[18:19] op_sel_hi:[1,0,1]
	v_pk_fma_f32 v[8:9], v[56:57], v[80:81], v[8:9] op_sel:[0,1,0]
	v_pk_fma_f32 v[10:11], v[58:59], v[80:81], v[10:11] op_sel:[0,1,0]
	v_pk_fma_f32 v[12:13], v[56:57], v[84:85], v[12:13] op_sel:[0,1,0]
	v_pk_fma_f32 v[14:15], v[58:59], v[84:85], v[14:15] op_sel:[0,1,0]
	v_pk_fma_f32 v[16:17], v[56:57], v[88:89], v[16:17] op_sel:[0,1,0]
	v_pk_fma_f32 v[18:19], v[58:59], v[88:89], v[18:19] op_sel:[0,1,0]
	v_pk_fma_f32 v[8:9], v[60:61], v[82:83], v[8:9] op_sel_hi:[1,0,1]
	v_pk_fma_f32 v[10:11], v[62:63], v[82:83], v[10:11] op_sel_hi:[1,0,1]
	v_pk_fma_f32 v[12:13], v[60:61], v[86:87], v[12:13] op_sel_hi:[1,0,1]
	v_pk_fma_f32 v[14:15], v[62:63], v[86:87], v[14:15] op_sel_hi:[1,0,1]
	v_pk_fma_f32 v[16:17], v[60:61], v[90:91], v[16:17] op_sel_hi:[1,0,1]
	v_pk_fma_f32 v[18:19], v[62:63], v[90:91], v[18:19] op_sel_hi:[1,0,1]
	v_pk_fma_f32 v[8:9], v[64:65], v[82:83], v[8:9] op_sel:[0,1,0]
	v_pk_fma_f32 v[10:11], v[66:67], v[82:83], v[10:11] op_sel:[0,1,0]
	v_pk_fma_f32 v[12:13], v[64:65], v[86:87], v[12:13] op_sel:[0,1,0]
	v_pk_fma_f32 v[14:15], v[66:67], v[86:87], v[14:15] op_sel:[0,1,0]
	v_pk_fma_f32 v[16:17], v[64:65], v[90:91], v[16:17] op_sel:[0,1,0]
	v_pk_fma_f32 v[18:19], v[66:67], v[90:91], v[18:19] op_sel:[0,1,0]
	ds_read_b128 v[80:83], v6 offset:112
	ds_read_b128 v[84:87], v6 offset:4208
	ds_read_b128 v[88:91], v6 offset:8304
	s_waitcnt vmcnt(4)
	s_waitcnt lgkmcnt(3)
	v_pk_fma_f32 v[8:9], v[20:21], v[68:69], v[8:9] op_sel_hi:[1,0,1]
	v_pk_fma_f32 v[10:11], v[22:23], v[68:69], v[10:11] op_sel_hi:[1,0,1]
	v_pk_fma_f32 v[12:13], v[20:21], v[72:73], v[12:13] op_sel_hi:[1,0,1]
	v_pk_fma_f32 v[14:15], v[22:23], v[72:73], v[14:15] op_sel_hi:[1,0,1]
	v_pk_fma_f32 v[16:17], v[20:21], v[76:77], v[16:17] op_sel_hi:[1,0,1]
	v_pk_fma_f32 v[18:19], v[22:23], v[76:77], v[18:19] op_sel_hi:[1,0,1]
	v_pk_fma_f32 v[8:9], v[24:25], v[68:69], v[8:9] op_sel:[0,1,0]
	v_pk_fma_f32 v[10:11], v[26:27], v[68:69], v[10:11] op_sel:[0,1,0]
	v_pk_fma_f32 v[12:13], v[24:25], v[72:73], v[12:13] op_sel:[0,1,0]
	v_pk_fma_f32 v[14:15], v[26:27], v[72:73], v[14:15] op_sel:[0,1,0]
	v_pk_fma_f32 v[16:17], v[24:25], v[76:77], v[16:17] op_sel:[0,1,0]
	v_pk_fma_f32 v[18:19], v[26:27], v[76:77], v[18:19] op_sel:[0,1,0]
	v_pk_fma_f32 v[8:9], v[28:29], v[70:71], v[8:9] op_sel_hi:[1,0,1]
	v_pk_fma_f32 v[10:11], v[30:31], v[70:71], v[10:11] op_sel_hi:[1,0,1]
	v_pk_fma_f32 v[12:13], v[28:29], v[74:75], v[12:13] op_sel_hi:[1,0,1]
	v_pk_fma_f32 v[14:15], v[30:31], v[74:75], v[14:15] op_sel_hi:[1,0,1]
	v_pk_fma_f32 v[16:17], v[28:29], v[78:79], v[16:17] op_sel_hi:[1,0,1]
	v_pk_fma_f32 v[18:19], v[30:31], v[78:79], v[18:19] op_sel_hi:[1,0,1]
	v_pk_fma_f32 v[8:9], v[32:33], v[70:71], v[8:9] op_sel:[0,1,0]
	v_pk_fma_f32 v[10:11], v[34:35], v[70:71], v[10:11] op_sel:[0,1,0]
	v_pk_fma_f32 v[12:13], v[32:33], v[74:75], v[12:13] op_sel:[0,1,0]
	v_pk_fma_f32 v[14:15], v[34:35], v[74:75], v[14:15] op_sel:[0,1,0]
	v_pk_fma_f32 v[16:17], v[32:33], v[78:79], v[16:17] op_sel:[0,1,0]
	v_pk_fma_f32 v[18:19], v[34:35], v[78:79], v[18:19] op_sel:[0,1,0]
	s_waitcnt vmcnt(0)
; #define LAS __attribute__((address_space(3)))
; __device__ __forceinline__ void p0_prologue(const Args& a, LAS unsigned char* lds, int G) {
;     ...
;         *(LAS f32x4*)(red + (wid * 3 + 0) * 256 + 4 * lane) = a0;
;         *(LAS f32x4*)(red + (wid * 3 + 1) * 256 + 4 * lane) = a1;
;         *(LAS f32x4*)(red + (wid * 3 + 2) * 256 + 4 * lane) = a2;
;         __syncthreads();
;         if (tid < 256) {
;             float r0 = 0.f, r1 = 0.f, r2 = 0.f;
; #pragma unroll
;             for (int w = 0; w < 8; ++w) { r0 += red[(w * 3 + 0) * 256 + tid]; r1 += red[(w * 3 + 1) * 256 + tid]; r2 += red[(w * 3 + 2) * 256 + tid]; }
	s_waitcnt lgkmcnt(0)
	v_pk_fma_f32 v[8:9], v[36:37], v[80:81], v[8:9] op_sel_hi:[1,0,1]
	v_pk_fma_f32 v[10:11], v[38:39], v[80:81], v[10:11] op_sel_hi:[1,0,1]
	v_pk_fma_f32 v[12:13], v[36:37], v[84:85], v[12:13] op_sel_hi:[1,0,1]
	v_pk_fma_f32 v[14:15], v[38:39], v[84:85], v[14:15] op_sel_hi:[1,0,1]
	v_pk_fma_f32 v[16:17], v[36:37], v[88:89], v[16:17] op_sel_hi:[1,0,1]
	v_pk_fma_f32 v[18:19], v[38:39], v[88:89], v[18:19] op_sel_hi:[1,0,1]
	v_pk_fma_f32 v[8:9], v[40:41], v[80:81], v[8:9] op_sel:[0,1,0]
	v_pk_fma_f32 v[10:11], v[42:43], v[80:81], v[10:11] op_sel:[0,1,0]
	v_pk_fma_f32 v[12:13], v[40:41], v[84:85], v[12:13] op_sel:[0,1,0]
	v_pk_fma_f32 v[14:15], v[42:43], v[84:85], v[14:15] op_sel:[0,1,0]
	v_pk_fma_f32 v[16:17], v[40:41], v[88:89], v[16:17] op_sel:[0,1,0]
	v_pk_fma_f32 v[18:19], v[42:43], v[88:89], v[18:19] op_sel:[0,1,0]
	v_pk_fma_f32 v[8:9], v[44:45], v[82:83], v[8:9] op_sel_hi:[1,0,1]
	v_pk_fma_f32 v[10:11], v[46:47], v[82:83], v[10:11] op_sel_hi:[1,0,1]
	v_pk_fma_f32 v[12:13], v[44:45], v[86:87], v[12:13] op_sel_hi:[1,0,1]
	v_pk_fma_f32 v[14:15], v[46:47], v[86:87], v[14:15] op_sel_hi:[1,0,1]
	v_pk_fma_f32 v[16:17], v[44:45], v[90:91], v[16:17] op_sel_hi:[1,0,1]
	v_pk_fma_f32 v[18:19], v[46:47], v[90:91], v[18:19] op_sel_hi:[1,0,1]
	v_pk_fma_f32 v[8:9], v[48:49], v[82:83], v[8:9] op_sel:[0,1,0]
	v_pk_fma_f32 v[10:11], v[50:51], v[82:83], v[10:11] op_sel:[0,1,0]
	v_pk_fma_f32 v[12:13], v[48:49], v[86:87], v[12:13] op_sel:[0,1,0]
	v_pk_fma_f32 v[14:15], v[50:51], v[86:87], v[14:15] op_sel:[0,1,0]
	v_pk_fma_f32 v[16:17], v[48:49], v[90:91], v[16:17] op_sel:[0,1,0]
	v_pk_fma_f32 v[18:19], v[50:51], v[90:91], v[18:19] op_sel:[0,1,0]
	s_lshl_b32 s4, s14, 2
	v_add_u32_e32 v7, s4, v3
	v_mul_u32_u24_e32 v7, 0x300, v7
	v_lshl_add_u32 v7, v4, 4, v7
	ds_write_b128 v7, v[8:11] offset:12288
	ds_write_b128 v7, v[12:15] offset:12544
	ds_write_b128 v7, v[16:19] offset:12800
	s_waitcnt lgkmcnt(0)
	s_barrier
	v_cmp_gt_u32_e32 vcc, 48, v206
	s_and_saveexec_b64 s[54:55], vcc
	s_cbranch_execz .Lgemv_red_done
	v_lshrrev_b32_e32 v3, 4, v206
	v_and_b32_e32 v4, 15, v206
	v_lshlrev_b32_e32 v7, 8, v3
	v_lshl_add_u32 v7, v4, 4, v7
	v_readlane_b32 s56, v252, 27
	v_readlane_b32 s57, v252, 28
	s_mul_i32 s4, s12, 0x6000
	s_add_u32 s4, s4, s52
	v_lshlrev_b32_e32 v5, 4, v4
	v_add_u32_e32 v5, s4, v5
	s_nop 2
	global_load_dwordx4 v[80:83], v5, s[56:57]
	v_mov_b32_e32 v8, 0
	v_mov_b32_e32 v9, 0
	v_mov_b32_e32 v10, 0
	v_mov_b32_e32 v11, 0
	ds_read_b128 v[20:23], v7 offset:12288
	ds_read_b128 v[24:27], v7 offset:13056
	ds_read_b128 v[28:31], v7 offset:13824
	ds_read_b128 v[32:35], v7 offset:14592
	ds_read_b128 v[36:39], v7 offset:15360
	ds_read_b128 v[40:43], v7 offset:16128
	ds_read_b128 v[44:47], v7 offset:16896
	ds_read_b128 v[48:51], v7 offset:17664
	s_waitcnt lgkmcnt(7)
	v_pk_add_f32 v[8:9], v[8:9], v[20:21]
	v_pk_add_f32 v[10:11], v[10:11], v[22:23]
	s_waitcnt lgkmcnt(6)
	v_pk_add_f32 v[8:9], v[8:9], v[24:25]
	v_pk_add_f32 v[10:11], v[10:11], v[26:27]
	s_waitcnt lgkmcnt(5)
	v_pk_add_f32 v[8:9], v[8:9], v[28:29]
	v_pk_add_f32 v[10:11], v[10:11], v[30:31]
	s_waitcnt lgkmcnt(4)
	v_pk_add_f32 v[8:9], v[8:9], v[32:33]
	v_pk_add_f32 v[10:11], v[10:11], v[34:35]
	s_waitcnt lgkmcnt(3)
	v_pk_add_f32 v[8:9], v[8:9], v[36:37]
	v_pk_add_f32 v[10:11], v[10:11], v[38:39]
	s_waitcnt lgkmcnt(2)
	v_pk_add_f32 v[8:9], v[8:9], v[40:41]
	v_pk_add_f32 v[10:11], v[10:11], v[42:43]
	s_waitcnt lgkmcnt(1)
	v_pk_add_f32 v[8:9], v[8:9], v[44:45]
	v_pk_add_f32 v[10:11], v[10:11], v[46:47]
	s_waitcnt lgkmcnt(0)
	v_pk_add_f32 v[8:9], v[8:9], v[48:49]
	v_pk_add_f32 v[10:11], v[10:11], v[50:51]
	ds_read_b128 v[20:23], v7 offset:18432
	ds_read_b128 v[24:27], v7 offset:19200
	ds_read_b128 v[28:31], v7 offset:19968
	ds_read_b128 v[32:35], v7 offset:20736
	ds_read_b128 v[36:39], v7 offset:21504
	ds_read_b128 v[40:43], v7 offset:22272
	ds_read_b128 v[44:47], v7 offset:23040
	ds_read_b128 v[48:51], v7 offset:23808
	s_waitcnt lgkmcnt(7)
	v_pk_add_f32 v[8:9], v[8:9], v[20:21]
	v_pk_add_f32 v[10:11], v[10:11], v[22:23]
	s_waitcnt lgkmcnt(6)
	v_pk_add_f32 v[8:9], v[8:9], v[24:25]
	v_pk_add_f32 v[10:11], v[10:11], v[26:27]
	s_waitcnt lgkmcnt(5)
	v_pk_add_f32 v[8:9], v[8:9], v[28:29]
	v_pk_add_f32 v[10:11], v[10:11], v[30:31]
	s_waitcnt lgkmcnt(4)
	v_pk_add_f32 v[8:9], v[8:9], v[32:33]
	v_pk_add_f32 v[10:11], v[10:11], v[34:35]
	s_waitcnt lgkmcnt(3)
	v_pk_add_f32 v[8:9], v[8:9], v[36:37]
	v_pk_add_f32 v[10:11], v[10:11], v[38:39]
	s_waitcnt lgkmcnt(2)
	v_pk_add_f32 v[8:9], v[8:9], v[40:41]
	v_pk_add_f32 v[10:11], v[10:11], v[42:43]
	s_waitcnt lgkmcnt(1)
	v_pk_add_f32 v[8:9], v[8:9], v[44:45]
	v_pk_add_f32 v[10:11], v[10:11], v[46:47]
	s_waitcnt lgkmcnt(0)
; #define LAS __attribute__((address_space(3)))
; __device__ __forceinline__ void p0_prologue(const Args& a, LAS unsigned char* lds, int G) {
;     ...
;         if (tid < 256) {
;             float r0 = 0.f, r1 = 0.f, r2 = 0.f;
; #pragma unroll
;             for (int w = 0; w < 8; ++w) { r0 += red[(w * 3 + 0) * 256 + tid]; r1 += red[(w * 3 + 1) * 256 + tid]; r2 += red[(w * 3 + 2) * 256 + tid]; }
;             const float bias = a.b_mod[layer * 6144 + c0 + tid];
;             mod[(layer * 2 + 0) * 6144 + c0 + tid] = r0 + bias;
;             mod[(layer * 2 + 1) * 6144 + c0 + tid] = r1 + bias;
;             if (layer == 0 && c0 < 2048) modc[c0 + tid] = r2 + bias;
;         }
;     }
;     __syncthreads();
;     LAS float* scr = (LAS float*)(lds + wid * 16384);
;     const int gw = blockIdx.x * NWAVES + wid, NGW = G * NWAVES;
;     for (int it = gw; it < NP0_ITEMS; it += NGW) transpose_dispatch(a, it, scr, lane);
	v_pk_add_f32 v[8:9], v[8:9], v[48:49]
	v_pk_add_f32 v[10:11], v[10:11], v[50:51]
	ds_read_b128 v[20:23], v7 offset:24576
	ds_read_b128 v[24:27], v7 offset:25344
	ds_read_b128 v[28:31], v7 offset:26112
	ds_read_b128 v[32:35], v7 offset:26880
	ds_read_b128 v[36:39], v7 offset:27648
	ds_read_b128 v[40:43], v7 offset:28416
	ds_read_b128 v[44:47], v7 offset:29184
	ds_read_b128 v[48:51], v7 offset:29952
	s_waitcnt lgkmcnt(7)
	v_pk_add_f32 v[8:9], v[8:9], v[20:21]
	v_pk_add_f32 v[10:11], v[10:11], v[22:23]
	s_waitcnt lgkmcnt(6)
	v_pk_add_f32 v[8:9], v[8:9], v[24:25]
	v_pk_add_f32 v[10:11], v[10:11], v[26:27]
	s_waitcnt lgkmcnt(5)
	v_pk_add_f32 v[8:9], v[8:9], v[28:29]
	v_pk_add_f32 v[10:11], v[10:11], v[30:31]
	s_waitcnt lgkmcnt(4)
	v_pk_add_f32 v[8:9], v[8:9], v[32:33]
	v_pk_add_f32 v[10:11], v[10:11], v[34:35]
	s_waitcnt lgkmcnt(3)
	v_pk_add_f32 v[8:9], v[8:9], v[36:37]
	v_pk_add_f32 v[10:11], v[10:11], v[38:39]
	s_waitcnt lgkmcnt(2)
	v_pk_add_f32 v[8:9], v[8:9], v[40:41]
	v_pk_add_f32 v[10:11], v[10:11], v[42:43]
	s_waitcnt lgkmcnt(1)
	v_pk_add_f32 v[8:9], v[8:9], v[44:45]
	v_pk_add_f32 v[10:11], v[10:11], v[46:47]
	s_waitcnt lgkmcnt(0)
	v_pk_add_f32 v[8:9], v[8:9], v[48:49]
	v_pk_add_f32 v[10:11], v[10:11], v[50:51]
	ds_read_b128 v[20:23], v7 offset:30720
	ds_read_b128 v[24:27], v7 offset:31488
	ds_read_b128 v[28:31], v7 offset:32256
	ds_read_b128 v[32:35], v7 offset:33024
	ds_read_b128 v[36:39], v7 offset:33792
	ds_read_b128 v[40:43], v7 offset:34560
	ds_read_b128 v[44:47], v7 offset:35328
	ds_read_b128 v[48:51], v7 offset:36096
	s_waitcnt lgkmcnt(7)
	v_pk_add_f32 v[8:9], v[8:9], v[20:21]
	v_pk_add_f32 v[10:11], v[10:11], v[22:23]
	s_waitcnt lgkmcnt(6)
	v_pk_add_f32 v[8:9], v[8:9], v[24:25]
	v_pk_add_f32 v[10:11], v[10:11], v[26:27]
	s_waitcnt lgkmcnt(5)
	v_pk_add_f32 v[8:9], v[8:9], v[28:29]
	v_pk_add_f32 v[10:11], v[10:11], v[30:31]
	s_waitcnt lgkmcnt(4)
	v_pk_add_f32 v[8:9], v[8:9], v[32:33]
	v_pk_add_f32 v[10:11], v[10:11], v[34:35]
	s_waitcnt lgkmcnt(3)
	v_pk_add_f32 v[8:9], v[8:9], v[36:37]
	v_pk_add_f32 v[10:11], v[10:11], v[38:39]
	s_waitcnt lgkmcnt(2)
	v_pk_add_f32 v[8:9], v[8:9], v[40:41]
	v_pk_add_f32 v[10:11], v[10:11], v[42:43]
	s_waitcnt lgkmcnt(1)
	v_pk_add_f32 v[8:9], v[8:9], v[44:45]
	v_pk_add_f32 v[10:11], v[10:11], v[46:47]
	s_waitcnt lgkmcnt(0)
	v_pk_add_f32 v[8:9], v[8:9], v[48:49]
	v_pk_add_f32 v[10:11], v[10:11], v[50:51]
	s_waitcnt vmcnt(0)
	v_pk_add_f32 v[8:9], v[8:9], v[80:81]
	v_pk_add_f32 v[10:11], v[10:11], v[82:83]
	v_lshl_add_u32 v6, v3, 0, 0
	s_lshl_b32 s4, s12, 1
	v_add_u32_e32 v6, s4, v6
	v_mul_u32_u24_e32 v6, 0x6000, v6
	v_lshlrev_b32_e32 v5, 4, v4
	v_add3_u32 v6, v6, v5, s52
	v_cmp_gt_u32_e32 vcc, 2, v3
	s_and_saveexec_b64 s[58:59], vcc
	global_store_dwordx4 v6, v[8:11], s[96:97]
	s_or_b64 exec, exec, s[58:59]
	s_cmp_eq_u32 s12, 0
	s_cselect_b64 s[58:59], -1, 0
	s_cmp_lt_u32 s13, 0x800
	s_cselect_b64 s[60:61], -1, 0
	s_and_b64 s[58:59], s[58:59], s[60:61]
	v_cmp_eq_u32_e32 vcc, 2, v3
	s_and_b64 vcc, vcc, s[58:59]
	s_and_saveexec_b64 s[58:59], vcc
	v_add_u32_e32 v6, s52, v5
	global_store_dwordx4 v6, v[8:11], s[94:95]
	s_or_b64 exec, exec, s[58:59]
.Lgemv_red_done:
	s_or_b64 exec, exec, s[54:55]
	s_branch .Lgemv_latch
.LBB0_25:
	s_sub_i32 s100, s2, 32
	s_lshl_b32 s0, s100, 3
	s_add_i32 s10, s14, s0
	s_cmpk_gt_u32 s10, 0x57f
	s_barrier
	s_cbranch_scc1 .LBB0_36
	v_lshlrev_b32_e32 v2, 3, v206
	s_lshl_b32 s0, s14, 14
	v_lshrrev_b32_e32 v28, 5, v1
	v_lshrrev_b32_e32 v1, 3, v1
	v_and_b32_e32 v2, 56, v2
	s_add_i32 s4, s0, 0
	v_mul_u32_u24_e32 v3, 0x84, v2
	v_lshlrev_b32_e32 v4, 2, v1
	v_add3_u32 v29, s4, v3, v4
	v_lshlrev_b32_e32 v2, 1, v2
	v_mov_b32_e32 v3, 0
	v_lshl_add_u64 v[4:5], s[34:35], 0, v[2:3]
	v_lshl_add_u64 v[8:9], s[90:91], 0, v[2:3]
	v_mul_u32_u24_e32 v2, 0x84, v28
	v_or_b32_e32 v2, s0, v2
	s_lshl_b32 s0, s100, 8
	s_lshl_b32 s4, s14, 5
	v_and_b32_e32 v6, 31, v206
	v_readlane_b32 s16, v252, 1
	s_add_i32 s12, s0, s4
	s_lshl_b32 s0, s100, 4
	s_lshl_b32 s4, s14, 1
	v_lshlrev_b32_e32 v10, 2, v6
	v_mov_b32_e32 v11, v3
	v_readlane_b32 s26, v252, 11
	v_readlane_b32 s27, v252, 12
	s_add_i32 s0, s0, s4
	s_lshl_b32 s11, s86, 3
	s_mov_b32 s1, 0
	v_or_b32_e32 v30, 8, v1
	v_or_b32_e32 v31, 16, v1
	v_or_b32_e32 v32, 24, v1
	v_lshl_add_u64 v[6:7], s[26:27], 0, v[10:11]
	v_add3_u32 v33, v2, v10, 0
	v_lshl_add_u64 v[10:11], s[40:41], 0, v[10:11]
	s_lshl_b32 s13, s86, 8
	v_or_b32_e32 v34, 14, v28
	s_add_i32 s14, s0, 0x1f900
	s_lshl_b32 s15, s86, 4
	v_or_b32_e32 v35, 12, v28
	v_or_b32_e32 v36, 10, v28
	v_or_b32_e32 v37, 8, v28
	v_or_b32_e32 v38, 6, v28
	v_or_b32_e32 v39, 4, v28
	v_or_b32_e32 v40, 2, v28
	s_movk_i32 s16, 0x1c00
	v_readlane_b32 s17, v252, 2
	v_readlane_b32 s18, v252, 3
	v_readlane_b32 s19, v252, 4
	v_readlane_b32 s20, v252, 5
	v_readlane_b32 s21, v252, 6
	v_readlane_b32 s22, v252, 7
	v_readlane_b32 s23, v252, 8
	v_readlane_b32 s24, v252, 9
	v_readlane_b32 s25, v252, 10
	v_readlane_b32 s28, v252, 13
	v_readlane_b32 s29, v252, 14
	v_readlane_b32 s30, v252, 15
	v_readlane_b32 s31, v252, 16
	s_branch .LBB0_28
